# adds: SSD sample unit requests the next queue index before its 32 state stores (fetch no longer waits for the store drain)
# baseline (speedup 1.0000x reference)
.LBB0_715:
	ds_write_b128 v196, v[102:105]
	ds_write_b128 v197, v[110:113]
	ds_write_b128 v198, v[106:109] offset:17408
	v_and_b32_e32 v51, 7, v167
	ds_write_b128 v199, v[114:117] offset:17408
	s_and_saveexec_b64 s[34:35], s[70:71]
	s_cbranch_execz .LBB0_718
	v_cmp_eq_u32_e32 vcc, 0, v51
	global_store_dwordx4 v[212:213], v[126:129], off
	s_nop 1
	v_lshl_add_u64 v[212:213], s[98:99], 1, v[212:213]
	s_and_b64 exec, exec, vcc
	s_cbranch_execz .LBB0_718
	global_store_dword v[214:215], v166, off
	v_lshl_add_u64 v[214:215], v[214:215], 0, s[100:101]

.LBB0_877:
	s_mov_b32 s83, 0
	s_add_u32 s3, s84, 0x5e48000
	s_addc_u32 s38, s85, 0
	s_add_u32 s39, s86, 0x700000
	s_addc_u32 s40, s87, 0
	s_add_u32 s41, s86, 0x21d00000
	s_addc_u32 s42, s87, 0
	s_add_u32 s43, s86, 0x9200000
	s_addc_u32 s44, s87, 0
	s_add_i32 s46, 0, 0x23d40
	v_or_b32_e32 v138, 0x2400, v0
	s_mov_b32 s19, 0
	v_or_b32_e32 v1, 0x200, v0
	s_lshl_b32 s45, s33, 10
	v_mov_b32_e32 v141, 0
	s_waitcnt vmcnt(9)
	v_mov_b32_e32 v157, s46
	s_movk_i32 s47, 0x1000
	s_movk_i32 s48, 0x2000
	s_movk_i32 s49, 0x3000
	s_movk_i32 s50, 0x4000
	s_movk_i32 s51, 0x5000
	s_movk_i32 s24, 0x6000
	s_waitcnt vmcnt(7)
	v_mov_b32_e32 v158, 0x3ecc95a3
	s_movk_i32 s25, 0x13f
	s_mov_b64 s[28:29], 0x800
	s_mov_b32 s26, 0xaaaaaaab
	s_mov_b32 s27, 0x1080000
	s_mov_b32 s68, 0xb400000
	v_mov_b32_e32 v142, 0x3f317218
	v_mov_b32_e32 v159, 0x7f800000
	s_waitcnt vmcnt(6)
	v_mov_b32_e32 v160, 0x7fc00000
	s_waitcnt vmcnt(5)
	v_mov_b32_e32 v161, 0xff800000
	v_mov_b32_e32 v162, 0x300
	v_mov_b32_e32 v163, 0x2000
	s_branch .LBB0_881

.LBB0_881:
	s_mov_b64 s[0:1], exec
	v_readlane_b32 s4, v254, 7
	v_readlane_b32 s5, v254, 8
	s_and_b64 s[4:5], s[0:1], s[4:5]
	s_mov_b64 exec, s[4:5]
	s_cbranch_execz .LBB0_885
	s_mov_b64 s[6:7], exec
	v_mbcnt_lo_u32_b32 v2, s6, 0
	v_mbcnt_hi_u32_b32 v2, s7, v2
	v_cmp_eq_u32_e32 vcc, 0, v2
	s_and_saveexec_b64 s[4:5], vcc
	s_cbranch_execz .LBB0_884
	s_cmp_eq_u32 s83, 1
	s_cbranch_scc1 .Lq3_use_pf
	s_bcnt1_i32_b64 s6, s[6:7]
	v_mov_b32_e32 v3, s6
	global_atomic_add v3, v141, v3, s[86:87] offset:1024 sc0
	s_branch .LBB0_884
.Lq3_use_pf:
	v_mov_b32_e32 v3, v253
.LBB0_884:
	s_or_b64 exec, exec, s[4:5]
	s_cmp_eq_u32 s83, 1
	s_cbranch_scc1 .Lq3_w32
	s_waitcnt vmcnt(0)
	s_branch .Lq3_wdone
.Lq3_w32:
	s_waitcnt vmcnt(32)
.Lq3_wdone:
	v_readfirstlane_b32 s4, v3
	v_mov_b32_e32 v3, s46
	s_nop 0
	v_add_u32_e32 v2, s4, v2
	ds_write_b32 v3, v2
.LBB0_885:
	s_or_b64 exec, exec, s[0:1]
	s_mov_b32 s83, 0
	s_waitcnt lgkmcnt(0)
	s_barrier
	ds_read_b32 v2, v157
	s_movk_i32 s0, 0x287
	s_waitcnt lgkmcnt(0)
	s_barrier
	v_cmp_lt_i32_e32 vcc, s0, v2
	v_readfirstlane_b32 s69, v2
	s_mov_b64 s[0:1], -1
	s_cbranch_vccnz .LBB0_880
	s_cmpk_lt_i32 s69, 0x200
	s_cbranch_scc0 .LBB0_932
	s_and_b32 s15, s69, 3
	s_ashr_i32 s36, s69, 2
	s_lshl_b32 s10, s15, 3
	s_add_i32 s14, s33, s10
	s_lshl_b32 s0, s36, 5
	s_add_i32 s0, s14, s0
	s_ashr_i32 s37, s36, 31
	s_ashr_i32 s1, s0, 31
	v_readlane_b32 s52, v254, 9
	s_waitcnt vmcnt(4)
	v_mov_b32_e32 v164, v0
	s_lshl_b64 s[4:5], s[36:37], 2
	s_lshl_b64 s[6:7], s[0:1], 15
	v_readlane_b32 s58, v254, 15
	v_readlane_b32 s59, v254, 16
	v_bfe_u32 v167, v164, 5, 1
	s_add_u32 s6, s58, s6
	v_and_b32_e32 v168, 31, v164
	s_addc_u32 s7, s59, s7
	v_lshlrev_b32_e32 v140, 9, v167
	v_lshl_add_u64 v[2:3], s[6:7], 0, v[140:141]
	v_lshlrev_b32_e32 v140, 4, v168
	v_lshl_add_u64 v[94:95], v[2:3], 0, v[140:141]
	v_add_co_u32_e32 v2, vcc, s47, v94
	s_movk_i32 s6, 0x7000
	s_nop 0
	v_addc_co_u32_e32 v3, vcc, 0, v95, vcc
	s_waitcnt vmcnt(1)
	v_add_co_u32_e32 v110, vcc, s48, v94
	global_load_dwordx4 v[90:93], v[94:95], off nt
	global_load_dwordx4 v[86:89], v[94:95], off offset:1024 nt
	global_load_dwordx4 v[82:85], v[94:95], off offset:2048 nt
	global_load_dwordx4 v[78:81], v[94:95], off offset:3072 nt
	v_addc_co_u32_e32 v111, vcc, 0, v95, vcc
	v_add_co_u32_e32 v4, vcc, s49, v94
	global_load_dwordx4 v[74:77], v[2:3], off offset:1024 nt
	global_load_dwordx4 v[70:73], v[2:3], off offset:2048 nt
	global_load_dwordx4 v[66:69], v[110:111], off nt
	global_load_dwordx4 v[62:65], v[110:111], off offset:1024 nt
	global_load_dwordx4 v[58:61], v[110:111], off offset:2048 nt
	global_load_dwordx4 v[54:57], v[110:111], off offset:3072 nt
	v_addc_co_u32_e32 v5, vcc, 0, v95, vcc
	v_add_co_u32_e32 v6, vcc, s50, v94
	s_add_u32 s8, s4, 0x4000
	s_nop 0
	v_addc_co_u32_e32 v7, vcc, 0, v95, vcc
	v_add_co_u32_e32 v96, vcc, s51, v94
	global_load_dwordx4 v[122:125], v[2:3], off offset:3072 nt
	global_load_dwordx4 v[26:29], v[4:5], off offset:1024 nt
	global_load_dwordx4 v[22:25], v[4:5], off offset:2048 nt
	global_load_dwordx4 v[18:21], v[4:5], off offset:3072 nt
	global_load_dwordx4 v[106:109], v[6:7], off offset:-4096 nt
	global_load_dwordx4 v[50:53], v[6:7], off nt
	global_load_dwordx4 v[46:49], v[6:7], off offset:1024 nt
	global_load_dwordx4 v[42:45], v[6:7], off offset:2048 nt
	v_addc_co_u32_e32 v97, vcc, 0, v95, vcc
	s_waitcnt vmcnt(18)
	v_add_co_u32_e32 v38, vcc, s24, v94
	s_movk_i32 s4, 0x17f
	s_nop 0
	v_addc_co_u32_e32 v39, vcc, 0, v95, vcc
	global_load_dwordx4 v[114:117], v[6:7], off offset:3072 nt
	global_load_dwordx4 v[14:17], v[38:39], off offset:-4096 nt
	global_load_dwordx4 v[10:13], v[96:97], off offset:1024 nt
	s_nop 0
	global_load_dwordx4 v[6:9], v[96:97], off offset:2048 nt
	global_load_dwordx4 v[2:5], v[38:39], off nt
	global_load_dwordx4 v[30:33], v[38:39], off offset:1024 nt
	global_load_dwordx4 v[34:37], v[38:39], off offset:2048 nt
	s_nop 0
	global_load_dwordx4 v[38:41], v[38:39], off offset:3072 nt
	v_add_co_u32_e32 v112, vcc, s6, v94
	s_addc_u32 s9, s5, 0
	s_nop 0
	v_addc_co_u32_e32 v113, vcc, 0, v95, vcc
	global_load_dwordx4 v[118:121], v[96:97], off offset:3072 nt
	s_nop 0
	global_load_dwordx4 v[94:97], v[112:113], off nt
	global_load_dwordx4 v[98:101], v[112:113], off offset:1024 nt
	global_load_dwordx4 v[102:105], v[112:113], off offset:2048 nt
	global_load_dwordx4 v[126:129], v[110:111], off offset:-4096 nt
	s_nop 0
	global_load_dwordx4 v[110:113], v[112:113], off offset:3072 nt
	v_cmp_lt_i32_e32 vcc, s4, v164
	v_readlane_b32 s53, v254, 10
	v_readlane_b32 s54, v254, 11
	v_readlane_b32 s55, v254, 12
	v_readlane_b32 s56, v254, 13
	v_readlane_b32 s57, v254, 14
	v_readlane_b32 s60, v254, 17
	v_readlane_b32 s61, v254, 18
	v_readlane_b32 s62, v254, 19
	v_readlane_b32 s63, v254, 20
	v_readlane_b32 s64, v254, 21
	v_readlane_b32 s65, v254, 22
	v_readlane_b32 s66, v254, 23
	v_readlane_b32 s67, v254, 24
	s_and_saveexec_b64 s[4:5], vcc
	s_xor_b64 s[4:5], exec, s[4:5]
	s_cbranch_execz .LBB0_893
	s_movk_i32 s6, 0x1a0
	v_cmp_gt_u32_e32 vcc, s6, v164
	s_and_saveexec_b64 s[6:7], vcc
	s_cbranch_execz .LBB0_892
	v_and_or_b32 v130, v164, 3, s8
	v_mov_b32_e32 v131, s9
	v_lshlrev_b64 v[130:131], 7, v[130:131]
	v_add_u32_e32 v132, 0xfffffe80, v164
	v_lshl_add_u64 v[130:131], s[20:21], 0, v[130:131]
	s_lshl_b32 s18, s10, 2
	v_lshrrev_b32_e32 v133, 2, v132
	v_and_b32_e32 v140, -4, v132
	v_lshl_add_u64 v[130:131], v[130:131], 0, s[18:19]
	v_lshl_add_u64 v[130:131], v[130:131], 0, v[140:141]
	v_add_u32_e32 v140, s10, v133
	global_load_dword v132, v[130:131], off
	v_lshl_add_u64 v[130:131], v[140:141], 2, s[76:77]
	global_load_dword v130, v[130:131], off
	s_mov_b32 s10, 0x41a00000
	s_waitcnt vmcnt(0)
	v_add_f32_e32 v130, v132, v130
	v_cmp_nlt_f32_e32 vcc, s10, v130
	s_and_saveexec_b64 s[10:11], vcc
	s_cbranch_execz .LBB0_891
	v_mul_f32_e32 v130, 0x3fb8aa3b, v130
	v_exp_f32_e32 v139, v130
	s_mov_b32 s12, 0x3f2aaaab
	v_add_f32_e32 v132, 1.0, v139
	v_frexp_mant_f32_e32 v134, v132
	v_cvt_f64_f32_e32 v[130:131], v132
	v_frexp_exp_i32_f64_e32 v130, v[130:131]
	v_cmp_gt_f32_e32 vcc, s12, v134
	v_add_f32_e32 v133, -1.0, v132
	v_sub_f32_e32 v135, v133, v132
	v_subbrev_co_u32_e32 v140, vcc, 0, v130, vcc
	v_sub_u32_e32 v130, 0, v140
	v_sub_f32_e32 v133, v139, v133
	v_add_f32_e32 v135, 1.0, v135
	v_ldexp_f32 v131, v132, v130
	v_add_f32_e32 v133, v133, v135
	v_add_f32_e32 v132, -1.0, v131
	v_add_f32_e32 v134, 1.0, v131
	v_ldexp_f32 v130, v133, v130
	v_add_f32_e32 v133, 1.0, v132
	v_add_f32_e32 v135, -1.0, v134
	v_sub_f32_e32 v133, v131, v133
	v_sub_f32_e32 v131, v131, v135
	v_add_f32_e32 v133, v130, v133
	v_add_f32_e32 v130, v130, v131
	v_add_f32_e32 v143, v134, v130
	v_rcp_f32_e32 v145, v143
	v_sub_f32_e32 v131, v143, v134
	v_sub_f32_e32 v144, v130, v131
	v_add_f32_e32 v131, v132, v133
	v_mul_f32_e32 v147, v131, v145
	v_sub_f32_e32 v130, v131, v132
	v_mul_f32_e32 v132, v143, v147
	v_fma_f32 v134, v147, v143, -v132
	v_fmac_f32_e32 v134, v147, v144
	v_sub_f32_e32 v146, v133, v130
	v_add_f32_e32 v130, v132, v134
	v_sub_f32_e32 v133, v131, v130
	v_pk_add_f32 v[136:137], v[130:131], v[132:133] neg_lo:[0,1] neg_hi:[0,1]
	v_mov_b32_e32 v135, v130
	v_pk_add_f32 v[130:131], v[136:137], v[134:135] neg_lo:[0,1] neg_hi:[0,1]
	s_mov_b32 s12, 0x3f317218
	v_add_f32_e32 v131, v146, v131
	v_add_f32_e32 v130, v130, v131
	v_add_f32_e32 v131, v133, v130
	v_mul_f32_e32 v146, v145, v131
	v_mul_f32_e32 v132, v143, v146
	v_fma_f32 v134, v146, v143, -v132
	v_fmac_f32_e32 v134, v146, v144
	v_sub_f32_e32 v133, v133, v131
	v_add_f32_e32 v143, v130, v133
	v_add_f32_e32 v130, v132, v134
	v_sub_f32_e32 v133, v131, v130
	v_pk_add_f32 v[136:137], v[130:131], v[132:133] neg_lo:[0,1] neg_hi:[0,1]
	v_mov_b32_e32 v135, v130
	v_pk_add_f32 v[130:131], v[136:137], v[134:135] neg_lo:[0,1] neg_hi:[0,1]
	s_nop 0
	v_add_f32_e32 v131, v143, v131
	v_add_f32_e32 v130, v130, v131
	v_add_f32_e32 v131, v147, v146
	v_add_f32_e32 v130, v133, v130
	v_sub_f32_e32 v132, v131, v147
	v_mul_f32_e32 v130, v145, v130
	v_sub_f32_e32 v132, v146, v132
	v_add_f32_e32 v132, v132, v130
	v_add_f32_e32 v134, v131, v132
	v_mul_f32_e32 v135, v134, v134
	v_fmamk_f32 v130, v135, 0x3e9b6dac, v158
	v_fmaak_f32 v143, v135, v130, 0x3f2aaada
	v_cvt_f32_i32_e32 v130, v140
	v_sub_f32_e32 v131, v134, v131
	v_sub_f32_e32 v131, v132, v131
	v_ldexp_f32 v136, v131, 1
	v_mul_f32_e32 v131, v134, v135
	v_ldexp_f32 v133, v134, 1
	v_pk_mul_f32 v[134:135], v[130:131], v[142:143]
	s_nop 0
	v_fma_f32 v132, v130, s12, -v134
	v_fmac_f32_e32 v132, 0xb102e308, v130
	v_pk_add_f32 v[130:131], v[134:135], v[132:133]
	s_mov_b32 s12, 0x7f800000
	v_sub_f32_e32 v133, v131, v133
	v_sub_f32_e32 v133, v135, v133
	v_add_f32_e32 v137, v136, v133
	v_mov_b32_e32 v136, v134
	v_pk_add_f32 v[134:135], v[130:131], v[134:135] neg_lo:[0,1] neg_hi:[0,1]
	v_pk_add_f32 v[144:145], v[130:131], v[136:137]
	v_mov_b32_e32 v133, v130
	v_mov_b32_e32 v135, v145
	v_pk_add_f32 v[146:147], v[132:133], v[134:135] neg_lo:[0,1] neg_hi:[0,1]
	v_pk_add_f32 v[132:133], v[132:133], v[134:135]
	v_mov_b32_e32 v136, v137
	v_pk_add_f32 v[134:135], v[132:133], v[130:131] op_sel:[1,0] op_sel_hi:[0,1] neg_lo:[0,1] neg_hi:[0,1]
	v_pk_add_f32 v[148:149], v[144:145], v[134:135] op_sel_hi:[1,0] neg_lo:[0,1] neg_hi:[0,1]
	v_mov_b32_e32 v144, v145
	v_mov_b32_e32 v145, v133
	v_pk_mov_b32 v[134:135], v[130:131], v[134:135] op_sel:[1,0]
	v_mov_b32_e32 v137, v130
	v_pk_add_f32 v[134:135], v[144:145], v[134:135] neg_lo:[0,1] neg_hi:[0,1]
	v_mov_b32_e32 v148, v146
	v_pk_add_f32 v[130:131], v[136:137], v[134:135] neg_lo:[0,1] neg_hi:[0,1]
	v_mov_b32_e32 v147, v133
	v_pk_add_f32 v[134:135], v[148:149], v[130:131]
	v_cmp_neq_f32_e32 vcc, s12, v139
	v_pk_add_f32 v[136:137], v[134:135], v[134:135] op_sel:[0,1] op_sel_hi:[1,0]
	s_mov_b32 s12, 0x33800000
	v_pk_add_f32 v[132:133], v[132:133], v[136:137] op_sel:[1,0] op_sel_hi:[0,1]
	v_mov_b32_e32 v135, v132
	v_pk_add_f32 v[144:145], v[134:135], v[146:147] neg_lo:[0,1] neg_hi:[0,1]
	v_mov_b32_e32 v131, v136
	v_sub_f32_e32 v133, v134, v144
	v_pk_add_f32 v[130:131], v[130:131], v[144:145] neg_lo:[0,1] neg_hi:[0,1]
	v_sub_f32_e32 v133, v146, v133
	v_add_f32_e32 v130, v130, v133
	v_add_f32_e32 v130, v130, v131
	v_add_f32_e32 v130, v132, v130
	v_cndmask_b32_e32 v130, v159, v130, vcc
	v_cmp_ngt_f32_e32 vcc, -1.0, v139
	s_nop 1
	v_cndmask_b32_e32 v130, v160, v130, vcc
	v_cmp_neq_f32_e32 vcc, -1.0, v139
	s_nop 1
	v_cndmask_b32_e32 v130, v161, v130, vcc
	v_cmp_lt_f32_e64 vcc, |v139|, s12
	s_nop 1
	v_cndmask_b32_e32 v130, v130, v139, vcc

.LBB0_931:
	s_mov_b64 s[98:99], exec
	v_readlane_b32 s100, v254, 7
	v_readlane_b32 s101, v254, 8
	s_mov_b32 s83, 1
	s_and_b64 s[100:101], s[98:99], s[100:101]
	s_mov_b64 exec, s[100:101]
	s_cbranch_execz .Lq3_pf_skip
	v_mov_b32_e32 v253, 1
	global_atomic_add v253, v141, v253, s[86:87] offset:1024 sc0
.Lq3_pf_skip:
	s_mov_b64 exec, s[98:99]
	s_lshl_b64 s[0:1], s[30:31], 2
	s_add_u32 s0, s3, s0
	s_addc_u32 s1, s38, s1
	v_lshlrev_b32_e32 v140, 2, v143
	s_waitcnt lgkmcnt(0)
	v_lshl_add_u64 v[130:131], s[0:1], 0, v[140:141]
	v_lshlrev_b32_e32 v140, 2, v139
	v_lshl_add_u64 v[130:131], v[130:131], 0, v[140:141]
	global_store_dwordx4 v[130:131], v[90:93], off nt
	global_store_dwordx4 v[130:131], v[86:89], off offset:1024 nt
	global_store_dwordx4 v[130:131], v[82:85], off offset:2048 nt
	global_store_dwordx4 v[130:131], v[78:81], off offset:3072 nt
	s_mov_b64 s[0:1], 0
	s_nop 0
	v_add_co_u32_e32 v78, vcc, s47, v130
	s_nop 1
	v_addc_co_u32_e32 v79, vcc, 0, v131, vcc
	v_add_co_u32_e32 v80, vcc, s48, v130
	s_nop 1
	v_addc_co_u32_e32 v81, vcc, 0, v131, vcc
	global_store_dwordx4 v[80:81], v[126:129], off offset:-4096 nt
	global_store_dwordx4 v[78:79], v[74:77], off offset:1024 nt
	global_store_dwordx4 v[78:79], v[70:73], off offset:2048 nt
	global_store_dwordx4 v[78:79], v[122:125], off offset:3072 nt
	global_store_dwordx4 v[80:81], v[66:69], off nt
	global_store_dwordx4 v[80:81], v[62:65], off offset:1024 nt
	global_store_dwordx4 v[80:81], v[58:61], off offset:2048 nt
	global_store_dwordx4 v[80:81], v[54:57], off offset:3072 nt
	s_nop 1
	v_add_co_u32_e32 v54, vcc, s49, v130
	s_nop 1
	v_addc_co_u32_e32 v55, vcc, 0, v131, vcc
	v_add_co_u32_e32 v56, vcc, s50, v130
	s_nop 1
	v_addc_co_u32_e32 v57, vcc, 0, v131, vcc
	global_store_dwordx4 v[56:57], v[106:109], off offset:-4096 nt
	global_store_dwordx4 v[54:55], v[26:29], off offset:1024 nt
	global_store_dwordx4 v[54:55], v[22:25], off offset:2048 nt
	global_store_dwordx4 v[54:55], v[18:21], off offset:3072 nt
	global_store_dwordx4 v[56:57], v[50:53], off nt
	global_store_dwordx4 v[56:57], v[46:49], off offset:1024 nt
	global_store_dwordx4 v[56:57], v[42:45], off offset:2048 nt
	global_store_dwordx4 v[56:57], v[114:117], off offset:3072 nt
	v_add_co_u32_e32 v18, vcc, s51, v130
	s_nop 1
	v_addc_co_u32_e32 v19, vcc, 0, v131, vcc
	v_add_co_u32_e32 v20, vcc, s24, v130
	s_nop 1
	v_addc_co_u32_e32 v21, vcc, 0, v131, vcc
	global_store_dwordx4 v[20:21], v[14:17], off offset:-4096 nt
	global_store_dwordx4 v[18:19], v[10:13], off offset:1024 nt
	global_store_dwordx4 v[18:19], v[6:9], off offset:2048 nt
	global_store_dwordx4 v[18:19], v[118:121], off offset:3072 nt
	global_store_dwordx4 v[20:21], v[2:5], off nt
	global_store_dwordx4 v[20:21], v[30:33], off offset:1024 nt
	global_store_dwordx4 v[20:21], v[34:37], off offset:2048 nt
	global_store_dwordx4 v[20:21], v[38:41], off offset:3072 nt
	v_add_co_u32_e32 v2, vcc, 0x7000, v130
	s_nop 1
	v_addc_co_u32_e32 v3, vcc, 0, v131, vcc
	global_store_dwordx4 v[2:3], v[94:97], off nt
	global_store_dwordx4 v[2:3], v[98:101], off offset:1024 nt
	global_store_dwordx4 v[2:3], v[102:105], off offset:2048 nt
	global_store_dwordx4 v[2:3], v[110:113], off offset:3072 nt
	s_barrier
